# v sweep end-of-step reduction: lane^32 / lane^16 stages by v_permlane32_swap / v_permlane16_swap + add instead of select pairs + ds_bpermute round trips (29 fewer instructions per step)
# speedup vs baseline: 1.0173x; 1.0136x over previous
.Lvsw_skip_gb:
	v_readlane_b32 s100, v252, s39
	v_readlane_b32 s101, v253, s39
	v_ashrrev_i32_e32 v139, 31, v138
	v_lshl_add_u32 v173, s18, 1, v145
	s_lshl_b32 s18, s11, 7
	v_lshlrev_b64 v[138:139], 10, v[138:139]
	v_lshl_add_u64 v[138:139], v[138:139], 0, s[18:19]
	s_lshl_b32 s18, s11, 21
	s_waitcnt lgkmcnt(7)
	v_lshlrev_b32_sdwa v72, v141, v153 dst_sel:DWORD dst_unused:UNUSED_PAD src0_sel:DWORD src1_sel:WORD_0
	s_waitcnt vmcnt(7)
	v_cvt_pk_f32_fp8_e32 v[36:37], v28
	v_cvt_pk_f32_fp8_sdwa v[38:39], v28 src0_sel:WORD_1
	v_cvt_pk_f32_fp8_e32 v[40:41], v29
	v_cvt_pk_f32_fp8_sdwa v[28:29], v29 src0_sel:WORD_1
	v_cvt_pk_f32_fp8_e32 v[42:43], v30
	v_cvt_pk_f32_fp8_sdwa v[44:45], v30 src0_sel:WORD_1
	v_cvt_pk_f32_fp8_e32 v[48:49], v31
	v_cvt_pk_f32_fp8_sdwa v[50:51], v31 src0_sel:WORD_1
	v_lshl_add_u64 v[162:163], v[32:33], 0, s[18:19]
	s_waitcnt vmcnt(6)
	v_cvt_pk_f32_fp8_e32 v[30:31], v20
	v_cvt_pk_f32_fp8_sdwa v[46:47], v20 src0_sel:WORD_1
	v_cvt_pk_f32_fp8_e32 v[52:53], v21
	v_cvt_pk_f32_fp8_sdwa v[54:55], v21 src0_sel:WORD_1
	v_cvt_pk_f32_fp8_e32 v[58:59], v22
	v_cvt_pk_f32_fp8_sdwa v[60:61], v22 src0_sel:WORD_1
	v_cvt_pk_f32_fp8_e32 v[68:69], v23
	v_cvt_pk_f32_fp8_sdwa v[70:71], v23 src0_sel:WORD_1
	v_lshl_add_u32 v154, s39, 8, v77
	v_or_b32_e32 v138, v138, v34
	v_lshl_add_u64 v[156:157], v[162:163], 0, v[72:73]
	s_waitcnt lgkmcnt(6)
	v_lshlrev_b32_sdwa v72, v141, v146 dst_sel:DWORD dst_unused:UNUSED_PAD src0_sel:DWORD src1_sel:WORD_0
	s_waitcnt vmcnt(5)
	v_cvt_pk_f32_fp8_e32 v[20:21], v24
	v_cvt_pk_f32_fp8_sdwa v[22:23], v24 src0_sel:WORD_1
	v_cvt_pk_f32_fp8_e32 v[56:57], v25
	v_cvt_pk_f32_fp8_sdwa v[24:25], v25 src0_sel:WORD_1
	v_cvt_pk_f32_fp8_e32 v[62:63], v26
	v_cvt_pk_f32_fp8_sdwa v[64:65], v26 src0_sel:WORD_1
	v_cvt_pk_f32_fp8_e32 v[78:79], v27
	v_cvt_pk_f32_fp8_sdwa v[80:81], v27 src0_sel:WORD_1
	ds_read_u16 v175, v173
	ds_read_u16 v179, v173 offset:16
	ds_read_u16 v181, v173 offset:32
	ds_read_u16 v183, v173 offset:48
	ds_read_u16 v185, v173 offset:64
	ds_read_u16 v187, v173 offset:80
	ds_read_u16 v189, v173 offset:96
	ds_read_u16 v191, v173 offset:112
	ds_read_u16 v160, v154
	ds_read_u16 v161, v154 offset:16
	ds_read_u16 v169, v154 offset:32
	ds_read_u16 v174, v154 offset:48
	ds_read_u16 v180, v154 offset:64
	ds_read_u16 v182, v154 offset:80
	ds_read_u16 v184, v154 offset:96
	ds_read_u16 v186, v154 offset:112
	ds_read_u16 v153, v173 offset:128
	ds_read_u16 v188, v154 offset:128
	ds_read_u16 v190, v154 offset:144
	ds_read_u16 v192, v154 offset:160
	ds_read_u16 v193, v154 offset:176
	ds_read_u16 v195, v154 offset:192
	ds_read_u16 v197, v154 offset:208
	ds_read_u16 v199, v154 offset:224
	ds_read_u16 v201, v154 offset:240
	v_lshlrev_b64 v[154:155], 2, v[138:139]
	v_lshl_add_u64 v[138:139], v[138:139], 1, s[64:65]
	v_lshl_add_u64 v[158:159], v[162:163], 0, v[72:73]
	s_waitcnt lgkmcnt(14)
	v_lshlrev_b32_sdwa v72, v141, v151 dst_sel:DWORD dst_unused:UNUSED_PAD src0_sel:DWORD src1_sel:WORD_0
	s_waitcnt vmcnt(4)
	v_cvt_pk_f32_fp8_e32 v[26:27], v12
	v_cvt_pk_f32_fp8_sdwa v[66:67], v12 src0_sel:WORD_1
	v_cvt_pk_f32_fp8_e32 v[82:83], v13
	v_cvt_pk_f32_fp8_sdwa v[12:13], v13 src0_sel:WORD_1
	v_cvt_pk_f32_fp8_e32 v[86:87], v14
	v_cvt_pk_f32_fp8_sdwa v[88:89], v14 src0_sel:WORD_1
	v_cvt_pk_f32_fp8_e32 v[92:93], v15
	v_cvt_pk_f32_fp8_sdwa v[94:95], v15 src0_sel:WORD_1
	ds_read_u16 v146, v173 offset:144
	ds_read_u16 v151, v173 offset:160
	v_lshl_add_u64 v[166:167], s[62:63], 0, v[154:155]
	global_load_dword v203, v[138:139], off
	v_lshlrev_b32_e32 v168, 16, v160
	v_lshlrev_b32_e32 v170, 16, v161
	v_lshl_add_u64 v[138:139], s[60:61], 0, v[154:155]
	global_load_dwordx4 v[154:157], v[156:157], off
	s_nop 0
	global_load_dwordx4 v[158:161], v[158:159], off
	v_lshl_add_u64 v[204:205], v[162:163], 0, v[72:73]
	v_lshlrev_b32_sdwa v72, v141, v152 dst_sel:DWORD dst_unused:UNUSED_PAD src0_sel:DWORD src1_sel:WORD_0
	v_lshlrev_b32_e32 v172, 16, v169
	v_pk_fma_f32 v[36:37], v[36:37], v[168:169], 0 op_sel_hi:[1,0,0]
	v_pk_fma_f32 v[38:39], v[38:39], v[168:169], 0 op_sel_hi:[1,0,0]
	v_pk_fma_f32 v[40:41], v[40:41], v[168:169], 0 op_sel_hi:[1,0,0]
	v_pk_fma_f32 v[28:29], v[28:29], v[168:169], 0 op_sel_hi:[1,0,0]
	v_pk_fma_f32 v[42:43], v[42:43], v[168:169], 0 op_sel_hi:[1,0,0]
	v_pk_fma_f32 v[44:45], v[44:45], v[168:169], 0 op_sel_hi:[1,0,0]
	v_pk_fma_f32 v[48:49], v[48:49], v[168:169], 0 op_sel_hi:[1,0,0]
	v_pk_fma_f32 v[50:51], v[50:51], v[168:169], 0 op_sel_hi:[1,0,0]
	v_lshl_add_u64 v[168:169], v[162:163], 0, v[72:73]
	v_lshlrev_b32_sdwa v72, v141, v147 dst_sel:DWORD dst_unused:UNUSED_PAD src0_sel:DWORD src1_sel:WORD_0
	s_waitcnt vmcnt(6)
	v_cvt_pk_f32_fp8_e32 v[14:15], v16
	v_cvt_pk_f32_fp8_sdwa v[84:85], v16 src0_sel:WORD_1
	v_cvt_pk_f32_fp8_e32 v[90:91], v17
	v_cvt_pk_f32_fp8_sdwa v[16:17], v17 src0_sel:WORD_1
	v_cvt_pk_f32_fp8_e32 v[96:97], v18
	v_cvt_pk_f32_fp8_sdwa v[98:99], v18 src0_sel:WORD_1
	v_cvt_pk_f32_fp8_e32 v[100:101], v19
	v_cvt_pk_f32_fp8_sdwa v[18:19], v19 src0_sel:WORD_1
	ds_read_u16 v152, v173 offset:176
	ds_read_u16 v147, v173 offset:192
	global_load_dwordx2 v[166:167], v[166:167], off
	v_pk_fma_f32 v[30:31], v[30:31], v[170:171], v[36:37] op_sel_hi:[1,0,1]
	v_pk_fma_f32 v[46:47], v[46:47], v[170:171], v[38:39] op_sel_hi:[1,0,1]
	v_pk_fma_f32 v[52:53], v[52:53], v[170:171], v[40:41] op_sel_hi:[1,0,1]
	v_pk_fma_f32 v[28:29], v[54:55], v[170:171], v[28:29] op_sel_hi:[1,0,1]
	v_pk_fma_f32 v[54:55], v[58:59], v[170:171], v[42:43] op_sel_hi:[1,0,1]
	v_pk_fma_f32 v[44:45], v[60:61], v[170:171], v[44:45] op_sel_hi:[1,0,1]
	v_pk_fma_f32 v[48:49], v[68:69], v[170:171], v[48:49] op_sel_hi:[1,0,1]
	v_pk_fma_f32 v[50:51], v[70:71], v[170:171], v[50:51] op_sel_hi:[1,0,1]
	global_load_dwordx4 v[36:39], v[204:205], off
	global_load_dwordx4 v[40:43], v[168:169], off
	v_lshl_add_u64 v[58:59], v[162:163], 0, v[72:73]
	v_lshlrev_b32_sdwa v72, v141, v148 dst_sel:DWORD dst_unused:UNUSED_PAD src0_sel:DWORD src1_sel:WORD_0
	s_waitcnt lgkmcnt(14)
	v_lshlrev_b32_e32 v174, 16, v174
	v_pk_fma_f32 v[20:21], v[20:21], v[172:173], v[30:31] op_sel_hi:[1,0,1]
	v_pk_fma_f32 v[22:23], v[22:23], v[172:173], v[46:47] op_sel_hi:[1,0,1]
	v_pk_fma_f32 v[30:31], v[56:57], v[172:173], v[52:53] op_sel_hi:[1,0,1]
	v_pk_fma_f32 v[24:25], v[24:25], v[172:173], v[28:29] op_sel_hi:[1,0,1]
	v_pk_fma_f32 v[28:29], v[62:63], v[172:173], v[54:55] op_sel_hi:[1,0,1]
	v_pk_fma_f32 v[44:45], v[64:65], v[172:173], v[44:45] op_sel_hi:[1,0,1]
	v_pk_fma_f32 v[46:47], v[78:79], v[172:173], v[48:49] op_sel_hi:[1,0,1]
	v_pk_fma_f32 v[48:49], v[80:81], v[172:173], v[50:51] op_sel_hi:[1,0,1]
	v_lshl_add_u64 v[50:51], v[162:163], 0, v[72:73]
	ds_read_u16 v148, v173 offset:208
	v_lshlrev_b32_sdwa v72, v141, v149 dst_sel:DWORD dst_unused:UNUSED_PAD src0_sel:DWORD src1_sel:WORD_0
	ds_read_u16 v149, v173 offset:224
	v_pk_fma_f32 v[20:21], v[26:27], v[174:175], v[20:21] op_sel_hi:[1,0,1]
	v_pk_fma_f32 v[26:27], v[82:83], v[174:175], v[30:31] op_sel_hi:[1,0,1]
	v_pk_fma_f32 v[12:13], v[12:13], v[174:175], v[24:25] op_sel_hi:[1,0,1]
	v_pk_fma_f32 v[24:25], v[86:87], v[174:175], v[28:29] op_sel_hi:[1,0,1]
	v_pk_fma_f32 v[28:29], v[88:89], v[174:175], v[44:45] op_sel_hi:[1,0,1]
	v_pk_fma_f32 v[30:31], v[92:93], v[174:175], v[46:47] op_sel_hi:[1,0,1]
	v_pk_fma_f32 v[52:53], v[94:95], v[174:175], v[48:49] op_sel_hi:[1,0,1]
	global_load_dwordx4 v[44:47], v[58:59], off
	s_nop 0
	global_load_dwordx4 v[48:51], v[50:51], off
	v_lshlrev_b32_e32 v180, 16, v180
	v_lshl_add_u64 v[54:55], v[162:163], 0, v[72:73]
	v_lshlrev_b32_sdwa v72, v141, v150 dst_sel:DWORD dst_unused:UNUSED_PAD src0_sel:DWORD src1_sel:WORD_0
	ds_read_u16 v150, v173 offset:240
	v_pk_fma_f32 v[12:13], v[16:17], v[180:181], v[12:13] op_sel_hi:[1,0,1]
	v_pk_fma_f32 v[16:17], v[96:97], v[180:181], v[24:25] op_sel_hi:[1,0,1]
	v_pk_fma_f32 v[24:25], v[98:99], v[180:181], v[28:29] op_sel_hi:[1,0,1]
	v_pk_fma_f32 v[18:19], v[18:19], v[180:181], v[52:53] op_sel_hi:[1,0,1]
	v_lshl_add_u64 v[28:29], v[162:163], 0, v[72:73]
	global_load_dwordx4 v[52:55], v[54:55], off
	s_nop 0
	global_load_dwordx4 v[56:59], v[28:29], off
	s_waitcnt vmcnt(12)
	v_cvt_pk_f32_fp8_e32 v[102:103], v4
	v_cvt_pk_f32_fp8_sdwa v[104:105], v4 src0_sel:WORD_1
	v_cvt_pk_f32_fp8_e32 v[106:107], v5
	v_cvt_pk_f32_fp8_sdwa v[4:5], v5 src0_sel:WORD_1
	v_cvt_pk_f32_fp8_e32 v[108:109], v6
	v_cvt_pk_f32_fp8_sdwa v[110:111], v6 src0_sel:WORD_1
	v_cvt_pk_f32_fp8_e32 v[114:115], v7
	v_cvt_pk_f32_fp8_sdwa v[116:117], v7 src0_sel:WORD_1
	s_waitcnt vmcnt(11)
	v_cvt_pk_f32_fp8_e32 v[6:7], v8
	v_cvt_pk_f32_fp8_sdwa v[112:113], v8 src0_sel:WORD_1
	v_cvt_pk_f32_fp8_e32 v[118:119], v9
	v_cvt_pk_f32_fp8_sdwa v[8:9], v9 src0_sel:WORD_1
	v_cvt_pk_f32_fp8_e32 v[120:121], v10
	v_cvt_pk_f32_fp8_sdwa v[122:123], v10 src0_sel:WORD_1
	v_cvt_pk_f32_fp8_e32 v[124:125], v11
	v_cvt_pk_f32_fp8_sdwa v[10:11], v11 src0_sel:WORD_1
	s_waitcnt vmcnt(10)
	v_cvt_pk_f32_fp8_e32 v[126:127], v0
	v_cvt_pk_f32_fp8_sdwa v[128:129], v0 src0_sel:WORD_1
	v_cvt_pk_f32_fp8_e32 v[130:131], v1
	v_cvt_pk_f32_fp8_sdwa v[0:1], v1 src0_sel:WORD_1
	s_and_b32 s18, s3, 0xe00000
	v_pk_fma_f32 v[22:23], v[66:67], v[174:175], v[22:23] op_sel_hi:[1,0,1]
	v_cvt_pk_f32_fp8_e32 v[132:133], v2
	v_cvt_pk_f32_fp8_sdwa v[134:135], v2 src0_sel:WORD_1
	v_cvt_pk_f32_fp8_e32 v[136:137], v3
	v_cvt_pk_f32_fp8_sdwa v[2:3], v3 src0_sel:WORD_1
	v_lshl_add_u64 v[164:165], v[32:33], 0, s[18:19]
	v_lshlrev_b32_e32 v182, 16, v182
	v_pk_fma_f32 v[14:15], v[14:15], v[180:181], v[20:21] op_sel_hi:[1,0,1]
	v_pk_fma_f32 v[20:21], v[84:85], v[180:181], v[22:23] op_sel_hi:[1,0,1]
	v_pk_fma_f32 v[22:23], v[90:91], v[180:181], v[26:27] op_sel_hi:[1,0,1]
	v_pk_fma_f32 v[26:27], v[100:101], v[180:181], v[30:31] op_sel_hi:[1,0,1]
	v_lshlrev_b32_e32 v72, 7, v175
	v_lshlrev_b32_e32 v184, 16, v184
	v_pk_fma_f32 v[4:5], v[4:5], v[182:183], v[12:13] op_sel_hi:[1,0,1]
	v_pk_fma_f32 v[12:13], v[108:109], v[182:183], v[16:17] op_sel_hi:[1,0,1]
	v_pk_fma_f32 v[16:17], v[110:111], v[182:183], v[24:25] op_sel_hi:[1,0,1]
	v_pk_fma_f32 v[24:25], v[114:115], v[182:183], v[26:27] op_sel_hi:[1,0,1]
	v_pk_fma_f32 v[18:19], v[116:117], v[182:183], v[18:19] op_sel_hi:[1,0,1]
	v_lshl_add_u64 v[26:27], v[164:165], 0, v[72:73]
	v_lshlrev_b32_e32 v72, 7, v179
	s_waitcnt lgkmcnt(14)
	v_lshlrev_b32_e32 v186, 16, v186
	v_pk_fma_f32 v[4:5], v[8:9], v[184:185], v[4:5] op_sel_hi:[1,0,1]
	v_pk_fma_f32 v[10:11], v[10:11], v[184:185], v[18:19] op_sel_hi:[1,0,1]
	v_lshl_add_u64 v[18:19], v[164:165], 0, v[72:73]
	v_lshlrev_b32_e32 v72, 7, v181
	v_pk_fma_f32 v[14:15], v[102:103], v[182:183], v[14:15] op_sel_hi:[1,0,1]
	v_pk_fma_f32 v[20:21], v[104:105], v[182:183], v[20:21] op_sel_hi:[1,0,1]
	v_pk_fma_f32 v[22:23], v[106:107], v[182:183], v[22:23] op_sel_hi:[1,0,1]
	v_pk_fma_f32 v[66:67], v[0:1], v[186:187], v[4:5] op_sel_hi:[1,0,1]
	v_lshl_add_u64 v[0:1], v[164:165], 0, v[72:73]
	v_lshlrev_b32_e32 v72, 7, v183
	v_pk_fma_f32 v[6:7], v[6:7], v[184:185], v[14:15] op_sel_hi:[1,0,1]
	v_pk_fma_f32 v[14:15], v[112:113], v[184:185], v[20:21] op_sel_hi:[1,0,1]
	v_pk_fma_f32 v[20:21], v[118:119], v[184:185], v[22:23] op_sel_hi:[1,0,1]
	v_pk_fma_f32 v[8:9], v[120:121], v[184:185], v[12:13] op_sel_hi:[1,0,1]
	v_pk_fma_f32 v[12:13], v[122:123], v[184:185], v[16:17] op_sel_hi:[1,0,1]
	v_pk_fma_f32 v[80:81], v[2:3], v[186:187], v[10:11] op_sel_hi:[1,0,1]
	v_lshl_add_u64 v[2:3], v[164:165], 0, v[72:73]
	v_lshlrev_b32_e32 v72, 7, v185
	v_pk_fma_f32 v[16:17], v[124:125], v[184:185], v[24:25] op_sel_hi:[1,0,1]
	v_pk_fma_f32 v[62:63], v[128:129], v[186:187], v[14:15] op_sel_hi:[1,0,1]
	v_pk_fma_f32 v[64:65], v[130:131], v[186:187], v[20:21] op_sel_hi:[1,0,1]
	v_pk_fma_f32 v[70:71], v[134:135], v[186:187], v[12:13] op_sel_hi:[1,0,1]
	global_load_dwordx4 v[28:31], v[26:27], off
	global_load_dwordx4 v[20:23], v[18:19], off
	s_nop 0
	global_load_dwordx4 v[24:27], v[0:1], off
	global_load_dwordx4 v[12:15], v[2:3], off
	v_lshl_add_u64 v[0:1], v[164:165], 0, v[72:73]
	v_lshlrev_b32_e32 v72, 7, v187
	v_lshl_add_u64 v[2:3], v[164:165], 0, v[72:73]
	v_lshlrev_b32_e32 v72, 7, v189
	v_pk_fma_f32 v[60:61], v[126:127], v[186:187], v[6:7] op_sel_hi:[1,0,1]
	v_pk_fma_f32 v[78:79], v[136:137], v[186:187], v[16:17] op_sel_hi:[1,0,1]
	global_load_dwordx4 v[16:19], v[0:1], off
	global_load_dwordx4 v[4:7], v[2:3], off
	v_lshl_add_u64 v[0:1], v[164:165], 0, v[72:73]
	v_lshlrev_b32_e32 v72, 7, v191
	v_lshl_add_u64 v[2:3], v[164:165], 0, v[72:73]
	v_pk_fma_f32 v[68:69], v[132:133], v[186:187], v[8:9] op_sel_hi:[1,0,1]
	global_load_dwordx4 v[8:11], v[0:1], off
	s_nop 0
	global_load_dwordx4 v[0:3], v[2:3], off
	s_waitcnt vmcnt(16)
	v_cvt_pk_f32_fp8_e32 v[82:83], v154
	v_cvt_pk_f32_fp8_sdwa v[84:85], v154 src0_sel:WORD_1
	v_cvt_pk_f32_fp8_e32 v[86:87], v155
	v_cvt_pk_f32_fp8_sdwa v[88:89], v155 src0_sel:WORD_1
	v_cvt_pk_f32_fp8_e32 v[90:91], v156
	v_cvt_pk_f32_fp8_sdwa v[92:93], v156 src0_sel:WORD_1
	v_cvt_pk_f32_fp8_e32 v[94:95], v157
	v_cvt_pk_f32_fp8_sdwa v[96:97], v157 src0_sel:WORD_1
	s_waitcnt vmcnt(15)
	v_cvt_pk_f32_fp8_e32 v[100:101], v158
	v_cvt_pk_f32_fp8_sdwa v[102:103], v158 src0_sel:WORD_1
	v_cvt_pk_f32_fp8_e32 v[104:105], v159
	v_cvt_pk_f32_fp8_sdwa v[106:107], v159 src0_sel:WORD_1
	v_cvt_pk_f32_fp8_e32 v[108:109], v160
	v_cvt_pk_f32_fp8_sdwa v[110:111], v160 src0_sel:WORD_1
	v_cvt_pk_f32_fp8_e32 v[112:113], v161
	v_cvt_pk_f32_fp8_sdwa v[114:115], v161 src0_sel:WORD_1
	s_waitcnt vmcnt(13)
	v_cvt_pk_f32_fp8_e32 v[116:117], v36
	v_cvt_pk_f32_fp8_sdwa v[118:119], v36 src0_sel:WORD_1
	v_cvt_pk_f32_fp8_e32 v[120:121], v37
	v_cvt_pk_f32_fp8_sdwa v[36:37], v37 src0_sel:WORD_1
	v_cvt_pk_f32_fp8_e32 v[122:123], v38
	v_cvt_pk_f32_fp8_sdwa v[124:125], v38 src0_sel:WORD_1
	v_cvt_pk_f32_fp8_e32 v[126:127], v39
	v_cvt_pk_f32_fp8_sdwa v[38:39], v39 src0_sel:WORD_1
	v_lshlrev_b32_e32 v188, 16, v188
	s_waitcnt vmcnt(12)
	v_cvt_pk_f32_fp8_e32 v[128:129], v40
	v_cvt_pk_f32_fp8_sdwa v[130:131], v40 src0_sel:WORD_1
	v_cvt_pk_f32_fp8_e32 v[132:133], v41
	v_cvt_pk_f32_fp8_sdwa v[40:41], v41 src0_sel:WORD_1
	v_cvt_pk_f32_fp8_e32 v[134:135], v42
	v_cvt_pk_f32_fp8_sdwa v[136:137], v42 src0_sel:WORD_1
	v_cvt_pk_f32_fp8_e32 v[154:155], v43
	v_cvt_pk_f32_fp8_sdwa v[42:43], v43 src0_sel:WORD_1
	s_waitcnt lgkmcnt(13)
	v_lshlrev_b32_e32 v190, 16, v190
	v_pk_fma_f32 v[60:61], v[82:83], v[188:189], v[60:61] op_sel_hi:[1,0,1]
	v_pk_fma_f32 v[62:63], v[84:85], v[188:189], v[62:63] op_sel_hi:[1,0,1]
	v_pk_fma_f32 v[64:65], v[86:87], v[188:189], v[64:65] op_sel_hi:[1,0,1]
	v_pk_fma_f32 v[66:67], v[88:89], v[188:189], v[66:67] op_sel_hi:[1,0,1]
	v_pk_fma_f32 v[68:69], v[90:91], v[188:189], v[68:69] op_sel_hi:[1,0,1]
	v_pk_fma_f32 v[70:71], v[92:93], v[188:189], v[70:71] op_sel_hi:[1,0,1]
	v_pk_fma_f32 v[78:79], v[94:95], v[188:189], v[78:79] op_sel_hi:[1,0,1]
	v_pk_fma_f32 v[80:81], v[96:97], v[188:189], v[80:81] op_sel_hi:[1,0,1]
	s_waitcnt vmcnt(11)
	v_cvt_pk_f32_fp8_e32 v[82:83], v44
	v_cvt_pk_f32_fp8_sdwa v[84:85], v44 src0_sel:WORD_1
	v_cvt_pk_f32_fp8_e32 v[86:87], v45
	v_cvt_pk_f32_fp8_sdwa v[44:45], v45 src0_sel:WORD_1
	v_cvt_pk_f32_fp8_e32 v[88:89], v46
	v_cvt_pk_f32_fp8_sdwa v[90:91], v46 src0_sel:WORD_1
	v_cvt_pk_f32_fp8_e32 v[92:93], v47
	v_cvt_pk_f32_fp8_sdwa v[46:47], v47 src0_sel:WORD_1
	s_waitcnt lgkmcnt(12)
	v_lshlrev_b32_e32 v192, 16, v192
	v_pk_fma_f32 v[60:61], v[100:101], v[190:191], v[60:61] op_sel_hi:[1,0,1]
	v_pk_fma_f32 v[62:63], v[102:103], v[190:191], v[62:63] op_sel_hi:[1,0,1]
	v_pk_fma_f32 v[64:65], v[104:105], v[190:191], v[64:65] op_sel_hi:[1,0,1]
	v_pk_fma_f32 v[66:67], v[106:107], v[190:191], v[66:67] op_sel_hi:[1,0,1]
	v_pk_fma_f32 v[68:69], v[108:109], v[190:191], v[68:69] op_sel_hi:[1,0,1]
	v_pk_fma_f32 v[70:71], v[110:111], v[190:191], v[70:71] op_sel_hi:[1,0,1]
	v_pk_fma_f32 v[78:79], v[112:113], v[190:191], v[78:79] op_sel_hi:[1,0,1]
	v_pk_fma_f32 v[80:81], v[114:115], v[190:191], v[80:81] op_sel_hi:[1,0,1]
	s_waitcnt vmcnt(10)
	v_cvt_pk_f32_fp8_e32 v[94:95], v48
	v_cvt_pk_f32_fp8_sdwa v[96:97], v48 src0_sel:WORD_1
	v_cvt_pk_f32_fp8_e32 v[100:101], v49
	v_cvt_pk_f32_fp8_sdwa v[48:49], v49 src0_sel:WORD_1
	v_cvt_pk_f32_fp8_e32 v[102:103], v50
	v_cvt_pk_f32_fp8_sdwa v[104:105], v50 src0_sel:WORD_1
	v_cvt_pk_f32_fp8_e32 v[106:107], v51
	v_cvt_pk_f32_fp8_sdwa v[50:51], v51 src0_sel:WORD_1
	s_waitcnt lgkmcnt(11)
	v_lshlrev_b32_e32 v194, 16, v193
	v_pk_fma_f32 v[60:61], v[116:117], v[192:193], v[60:61] op_sel_hi:[1,0,1]
	v_pk_fma_f32 v[62:63], v[118:119], v[192:193], v[62:63] op_sel_hi:[1,0,1]
	v_pk_fma_f32 v[64:65], v[120:121], v[192:193], v[64:65] op_sel_hi:[1,0,1]
	v_pk_fma_f32 v[36:37], v[36:37], v[192:193], v[66:67] op_sel_hi:[1,0,1]
	v_pk_fma_f32 v[66:67], v[122:123], v[192:193], v[68:69] op_sel_hi:[1,0,1]
	v_pk_fma_f32 v[68:69], v[124:125], v[192:193], v[70:71] op_sel_hi:[1,0,1]
	v_pk_fma_f32 v[70:71], v[126:127], v[192:193], v[78:79] op_sel_hi:[1,0,1]
	v_pk_fma_f32 v[38:39], v[38:39], v[192:193], v[80:81] op_sel_hi:[1,0,1]
	s_waitcnt vmcnt(9)
	v_cvt_pk_f32_fp8_e32 v[78:79], v52
	v_cvt_pk_f32_fp8_sdwa v[80:81], v52 src0_sel:WORD_1
	v_cvt_pk_f32_fp8_e32 v[108:109], v53
	v_cvt_pk_f32_fp8_sdwa v[52:53], v53 src0_sel:WORD_1
	v_cvt_pk_f32_fp8_e32 v[110:111], v54
	v_cvt_pk_f32_fp8_sdwa v[112:113], v54 src0_sel:WORD_1
	v_cvt_pk_f32_fp8_e32 v[114:115], v55
	v_cvt_pk_f32_fp8_sdwa v[54:55], v55 src0_sel:WORD_1
	s_waitcnt lgkmcnt(10)
	v_lshlrev_b32_e32 v196, 16, v195
	v_pk_fma_f32 v[60:61], v[128:129], v[194:195], v[60:61] op_sel_hi:[1,0,1]
	v_pk_fma_f32 v[62:63], v[130:131], v[194:195], v[62:63] op_sel_hi:[1,0,1]
	v_pk_fma_f32 v[64:65], v[132:133], v[194:195], v[64:65] op_sel_hi:[1,0,1]
	v_pk_fma_f32 v[36:37], v[40:41], v[194:195], v[36:37] op_sel_hi:[1,0,1]
	v_pk_fma_f32 v[40:41], v[134:135], v[194:195], v[66:67] op_sel_hi:[1,0,1]
	v_pk_fma_f32 v[66:67], v[136:137], v[194:195], v[68:69] op_sel_hi:[1,0,1]
	v_pk_fma_f32 v[68:69], v[154:155], v[194:195], v[70:71] op_sel_hi:[1,0,1]
	v_pk_fma_f32 v[38:39], v[42:43], v[194:195], v[38:39] op_sel_hi:[1,0,1]
	s_waitcnt vmcnt(8)
	v_cvt_pk_f32_fp8_e32 v[42:43], v56
	v_cvt_pk_f32_fp8_sdwa v[70:71], v56 src0_sel:WORD_1
	v_cvt_pk_f32_fp8_e32 v[116:117], v57
	v_cvt_pk_f32_fp8_sdwa v[56:57], v57 src0_sel:WORD_1
	v_cvt_pk_f32_fp8_e32 v[118:119], v58
	v_cvt_pk_f32_fp8_sdwa v[120:121], v58 src0_sel:WORD_1
	v_cvt_pk_f32_fp8_e32 v[122:123], v59
	v_cvt_pk_f32_fp8_sdwa v[58:59], v59 src0_sel:WORD_1
	s_waitcnt lgkmcnt(9)
	v_lshlrev_b32_e32 v198, 16, v197
	v_pk_fma_f32 v[60:61], v[82:83], v[196:197], v[60:61] op_sel_hi:[1,0,1]
	v_pk_fma_f32 v[62:63], v[84:85], v[196:197], v[62:63] op_sel_hi:[1,0,1]
	v_pk_fma_f32 v[64:65], v[86:87], v[196:197], v[64:65] op_sel_hi:[1,0,1]
	v_pk_fma_f32 v[36:37], v[44:45], v[196:197], v[36:37] op_sel_hi:[1,0,1]
	v_pk_fma_f32 v[40:41], v[88:89], v[196:197], v[40:41] op_sel_hi:[1,0,1]
	v_pk_fma_f32 v[44:45], v[90:91], v[196:197], v[66:67] op_sel_hi:[1,0,1]
	v_pk_fma_f32 v[66:67], v[92:93], v[196:197], v[68:69] op_sel_hi:[1,0,1]
	v_pk_fma_f32 v[38:39], v[46:47], v[196:197], v[38:39] op_sel_hi:[1,0,1]
	s_waitcnt lgkmcnt(8)
	v_lshlrev_b32_e32 v200, 16, v199
	v_pk_fma_f32 v[46:47], v[94:95], v[198:199], v[60:61] op_sel_hi:[1,0,1]
	v_pk_fma_f32 v[60:61], v[96:97], v[198:199], v[62:63] op_sel_hi:[1,0,1]
	v_pk_fma_f32 v[62:63], v[100:101], v[198:199], v[64:65] op_sel_hi:[1,0,1]
	v_pk_fma_f32 v[36:37], v[48:49], v[198:199], v[36:37] op_sel_hi:[1,0,1]
	v_pk_fma_f32 v[40:41], v[102:103], v[198:199], v[40:41] op_sel_hi:[1,0,1]
	v_pk_fma_f32 v[44:45], v[104:105], v[198:199], v[44:45] op_sel_hi:[1,0,1]
	v_pk_fma_f32 v[48:49], v[106:107], v[198:199], v[66:67] op_sel_hi:[1,0,1]
	v_pk_fma_f32 v[38:39], v[50:51], v[198:199], v[38:39] op_sel_hi:[1,0,1]
	s_waitcnt lgkmcnt(7)
	v_lshlrev_b32_e32 v202, 16, v201
	v_pk_fma_f32 v[46:47], v[78:79], v[200:201], v[46:47] op_sel_hi:[1,0,1]
	v_pk_fma_f32 v[50:51], v[80:81], v[200:201], v[60:61] op_sel_hi:[1,0,1]
	v_pk_fma_f32 v[60:61], v[108:109], v[200:201], v[62:63] op_sel_hi:[1,0,1]
	v_pk_fma_f32 v[36:37], v[52:53], v[200:201], v[36:37] op_sel_hi:[1,0,1]
	v_pk_fma_f32 v[40:41], v[110:111], v[200:201], v[40:41] op_sel_hi:[1,0,1]
	v_pk_fma_f32 v[44:45], v[112:113], v[200:201], v[44:45] op_sel_hi:[1,0,1]
	v_pk_fma_f32 v[48:49], v[114:115], v[200:201], v[48:49] op_sel_hi:[1,0,1]
	v_pk_fma_f32 v[38:39], v[54:55], v[200:201], v[38:39] op_sel_hi:[1,0,1]
	v_pk_fma_f32 v[42:43], v[42:43], v[202:203], v[46:47] op_sel_hi:[1,0,1]
	v_pk_fma_f32 v[46:47], v[70:71], v[202:203], v[50:51] op_sel_hi:[1,0,1]
	v_pk_fma_f32 v[50:51], v[116:117], v[202:203], v[60:61] op_sel_hi:[1,0,1]
	v_pk_fma_f32 v[36:37], v[56:57], v[202:203], v[36:37] op_sel_hi:[1,0,1]
	v_pk_fma_f32 v[40:41], v[118:119], v[202:203], v[40:41] op_sel_hi:[1,0,1]
	v_pk_fma_f32 v[44:45], v[120:121], v[202:203], v[44:45] op_sel_hi:[1,0,1]
	v_pk_fma_f32 v[48:49], v[122:123], v[202:203], v[48:49] op_sel_hi:[1,0,1]
	v_pk_fma_f32 v[38:39], v[58:59], v[202:203], v[38:39] op_sel_hi:[1,0,1]
	s_nop 1
	v_permlane32_swap_b32 v42, v40
	v_permlane32_swap_b32 v43, v41
	v_permlane32_swap_b32 v46, v44
	v_permlane32_swap_b32 v47, v45
	v_permlane32_swap_b32 v50, v48
	v_permlane32_swap_b32 v51, v49
	v_permlane32_swap_b32 v36, v38
	v_permlane32_swap_b32 v37, v39
	s_add_i32 s7, s41, 1
	v_pk_add_f32 v[40:41], v[42:43], v[40:41]
	v_pk_add_f32 v[44:45], v[46:47], v[44:45]
	v_pk_add_f32 v[48:49], v[50:51], v[48:49]
	v_pk_add_f32 v[38:39], v[36:37], v[38:39]
	v_lshlrev_b32_e32 v98, 16, v203
	v_and_b32_e32 v99, 0xffff0000, v203
	s_addk_i32 s6, 0x80
	v_permlane16_swap_b32 v40, v48
	v_permlane16_swap_b32 v41, v49
	v_permlane16_swap_b32 v44, v38
	v_permlane16_swap_b32 v45, v39
	v_pk_add_f32 v[36:37], v[44:45], v[38:39]
	v_pk_add_f32 v[38:39], v[40:41], v[48:49]
	s_add_i32 s3, s3, 0x10000
	v_cndmask_b32_e64 v40, v38, v36, s[0:1]
	v_cndmask_b32_e64 v41, v39, v37, s[0:1]
	v_cndmask_b32_e64 v37, v37, v39, s[0:1]
	v_cndmask_b32_e64 v36, v36, v38, s[0:1]
	v_mov_b32_dpp v38, v40 row_ror:8 row_mask:0xf bank_mask:0xf bound_ctrl:1
	v_mov_b32_dpp v39, v41 row_ror:8 row_mask:0xf bank_mask:0xf bound_ctrl:1
	v_pk_add_f32 v[166:167], v[166:167], s[100:101] op_sel_hi:[1,0] neg_lo:[0,1] neg_hi:[0,1]
	s_nop 0
	v_pk_mul_f32 v[166:167], v[166:167], s[100:101] op_sel:[0,1]
	s_nop 0
	v_pk_fma_f32 v[166:167], v[246:247], v[166:167], v[248:249]
	s_nop 0
	v_pk_fma_f32 v[98:99], v[166:167], s[58:59], v[98:99] op_sel_hi:[1,0,1]
	v_pk_add_f32 v[36:37], v[36:37], v[38:39]
	s_mov_b32 s41, s7
	s_cmpk_eq_i32 s7, 0x100
	v_pk_add_f32 v[36:37], v[98:99], v[36:37]
	global_store_dwordx2 v[138:139], v[36:37], off
	s_cbranch_scc0 .LBB0_1139
	s_waitcnt vmcnt(0)
	s_barrier
	v_lshlrev_b64 v[0:1], 12, v[74:75]
	v_lshl_add_u64 v[0:1], s[60:61], 0, v[0:1]
	v_mov_b32_e32 v77, v73
	v_lshl_add_u64 v[64:65], v[0:1], 0, v[76:77]
	v_lshl_add_u64 v[66:67], s[90:91], 0, v[76:77]
	v_lshl_add_u64 v[68:69], s[68:69], 0, v[76:77]
	s_mov_b64 s[100:101], 0x1000
	v_lshl_add_u64 v[64:65], v[64:65], 0, s[100:101]
	global_load_dwordx4 v[206:209], v[66:67], off
	global_load_dwordx4 v[210:213], v[66:67], off offset:1024
	global_load_dwordx4 v[214:217], v[66:67], off offset:2048
	global_load_dwordx4 v[218:221], v[66:67], off offset:3072
	global_load_dwordx4 v[222:225], v[68:69], off
	global_load_dwordx4 v[226:229], v[68:69], off offset:1024
	global_load_dwordx4 v[230:233], v[68:69], off offset:2048
	global_load_dwordx4 v[234:237], v[68:69], off offset:3072
	global_load_dwordx4 v[0:3], v[64:65], off offset:-4096
	global_load_dwordx4 v[4:7], v[64:65], off offset:-3072
	global_load_dwordx4 v[8:11], v[64:65], off offset:-2048
	global_load_dwordx4 v[12:15], v[64:65], off offset:-1024
	global_load_dwordx4 v[40:43], v[66:67], off
	global_load_dwordx4 v[40:43], v[66:67], off
	global_load_dwordx4 v[40:43], v[66:67], off
	global_load_dwordx4 v[40:43], v[66:67], off
	s_mov_b32 s0, 0
